# prologue phase: waves 4-7 run the RMSNorm(x) rows before the PEER/rope table items, waves 0-3 keep the original order, so bandwidth-bound and latency-bound work overlap on every CU
# baseline (speedup 1.0000x reference)
; #define LAS __attribute__((address_space(3)))
; __global__ void __launch_bounds__(NWAVES * 64, 2) mk_fwd(Params P) {
;     ...
;         { LAS float* scr = (LAS float*)(lds + wave * 16384);
;           constexpr int I_IN = (D / 64) * (NCOL / 32), I_OUT = (D / 64) * (D / 32);
;           for (int it = gw; it < I_IN + I_OUT; it += NGW) {
;               if (it < I_IN) p0_transpose_item<true>(P.w_in, D, NCOL, WIN_T, scr, it, lane);
;               else p0_transpose_item<false>(P.w_out, D, D, WOUT_T, scr, it - I_IN, lane);
;           } }
.LBB0_33:
	s_mov_b32 s98, 0
	v_readlane_b32 s0, v252, 0
	s_lshl_b32 s12, s0, 3
	v_readlane_b32 s0, v252, 9
	s_add_i32 s12, s12, s0
	s_lshl_b32 s0, s0, 14
	s_add_i32 s8, s0, 0
	s_cmpk_gt_i32 s12, 0x67f
	s_mov_b32 s1, 0
	s_cbranch_scc1 .LBB0_44
	v_lshlrev_b32_e32 v1, 3, v180
	v_and_b32_e32 v5, 31, v180
	v_lshrrev_b32_e32 v16, 3, v193
	v_and_b32_e32 v1, 56, v1
	v_mov_b32_e32 v7, 0
	v_readlane_b32 s4, v252, 7
	v_lshrrev_b32_e32 v2, 5, v193
	v_lshlrev_b32_e32 v10, 2, v5
	v_mul_u32_u24_e32 v3, 0x84, v1
	v_lshlrev_b32_e32 v6, 1, v1
	v_readlane_b32 s5, v252, 8
	v_lshlrev_b32_e32 v1, 2, v16
	v_mov_b32_e32 v11, v7
	v_add_u32_e32 v4, s8, v10
	s_movk_i32 s9, 0x84
	v_lshl_add_u64 v[8:9], s[4:5], 0, v[6:7]
	v_add3_u32 v17, s8, v3, v1
	v_or_b32_e32 v18, 8, v16
	v_or_b32_e32 v19, 16, v16
	v_or_b32_e32 v20, 24, v16
	v_lshl_add_u64 v[10:11], s[22:23], 0, v[10:11]
	v_lshl_add_u64 v[12:13], s[58:59], 0, v[6:7]
	v_bitop3_b32 v21, v16, 15, 24 bitop3:0xc8
	v_mov_b32_e32 v1, v2
	s_movk_i32 s13, 0x7fff
	s_mov_b32 s22, 0xffff0000
	s_movk_i32 s23, 0x2400
	s_mov_b32 s33, s12
	s_branch .LBB0_36

; #define LAS __attribute__((address_space(3)))
; __global__ void __launch_bounds__(NWAVES * 64, 2) mk_fwd(Params P) {
;     ...
;         { LAS float* scr = (LAS float*)(lds + wave * 16384);
;           constexpr int I_IN = (D / 64) * (NCOL / 32), I_OUT = (D / 64) * (D / 32);
;           for (int it = gw; it < I_IN + I_OUT; it += NGW) {
;               if (it < I_IN) p0_transpose_item<true>(P.w_in, D, NCOL, WIN_T, scr, it, lane);
;               else p0_transpose_item<false>(P.w_out, D, D, WOUT_T, scr, it - I_IN, lane);
;           } }
;         for (int rw = gw; rw < 2 * NEXP; rw += NGW) {
;     ...
;         { f32x4 wn[4];
; #pragma unroll
;           for (int j = 0; j < 4; ++j) wn[j] = *((const f32x4*)P.attn_norm + lane + 64 * j);
;           for (int m0 = gw * 4; m0 < M; m0 += NGW * 4) {
.LBB0_44:
	v_readlane_b32 s99, v252, 9
	s_cmp_lt_u32 s99, 4
	s_cbranch_scc1 .Lmy_c_go
	s_cmp_lg_u32 s98, 0
	s_cbranch_scc1 .Lmy_c_go
	s_mov_b32 s98, 1
	s_branch .Lmy_e_entry

; __global__ void __launch_bounds__(NWAVES * 64, 2) mk_fwd(Params P) {
;     ...
;         }
;         { f32x4 wn[4];
; #pragma unroll
;           for (int j = 0; j < 4; ++j) wn[j] = *((const f32x4*)P.attn_norm + lane + 64 * j);
;           for (int m0 = gw * 4; m0 < M; m0 += NGW * 4) {
;             f32x4 v[4][4];
; #pragma unroll
;             for (int q = 0; q < 4; ++q) { const f32x4* xr = (const f32x4*)xrow(P.xp, P.xs, m0 + q) + lane;
; #pragma unroll
;                 for (int j = 0; j < 4; ++j) v[q][j] = xr[64 * j]; }
.LBB0_208:
	s_or_b64 exec, exec, s[8:9]
	s_cmp_eq_u32 s98, 2
	s_cbranch_scc0 .Lmy_e_entry
	s_mov_b32 s98, 3
	s_mov_b64 s[90:91], s[72:73]
	s_branch .Lmy_f_go
.Lmy_e_entry:
	s_cmpk_lt_i32 s12, 0x3000
	v_mov_b32_e32 v19, 0
	s_mov_b64 s[90:91], s[72:73]
	s_cbranch_scc0 .LBB0_211
	v_lshlrev_b32_e32 v1, 4, v193
	global_load_dwordx4 v[2:5], v1, s[20:21] offset:3072
	global_load_dwordx4 v[6:9], v1, s[20:21] offset:2048
	global_load_dwordx4 v[10:13], v1, s[20:21] offset:1024
	global_load_dwordx4 v[14:17], v1, s[20:21]
	s_lshl_b32 s20, s12, 2
	s_lshl_b32 s22, s90, 5
	s_ashr_i32 s21, s20, 31
	s_ashr_i32 s23, s22, 31
	s_lshl_b64 s[0:1], s[20:21], 11
	s_add_u32 s0, s58, s0
	v_lshlrev_b32_e32 v18, 3, v193
	s_addc_u32 s1, s59, s1
	v_lshl_add_u64 v[18:19], s[0:1], 0, v[18:19]
	s_mov_b64 s[0:1], 0x5000000
	v_lshl_add_u64 v[82:83], v[18:19], 0, s[0:1]
	s_waitcnt lgkmcnt(0)
	s_lshl_b64 s[42:43], s[22:23], 11
	v_mov_b32_e32 v86, 0x358637bd
	s_mov_b32 s3, 0xf800000
	v_mov_b32_e32 v87, 0x260
	s_movk_i32 s12, 0x7fff
	s_mov_b32 s13, 0xffff0000
	s_movk_i32 s33, 0x1000

; __device__ __forceinline__ float wave_sum(float v) { v = row16_sum(v); v = swap_add16(v, v); return swap_add32(v, v); }
; #define BOTH(k) (IN(k) && IN((k) + 1))
; __global__ void __launch_bounds__(NWAVES * 64, 2) mk_fwd(Params P) {
;     ...
;           } }
;         if (bx == 0 && tid < 128) CTL[tid] = 0.f;
;         if (bx == 0 && wave == 2) { float a = P.lq1[lane] * P.lk1[lane], b = P.lq2[lane] * P.lk2[lane]; a = wave_sum(a); b = wave_sum(b); if (lane == 0) CTL[128] = expf(a) - expf(b) + LAMBDA_INIT; }
;         if (BOTH(0)) grid.sync();
.LBB0_211:
	s_cmp_eq_u32 s98, 1
	s_cbranch_scc0 .Lmy_f_go
	s_mov_b32 s98, 2
	v_readlane_b32 s0, v252, 0
	s_lshl_b32 s12, s0, 3
	v_readlane_b32 s0, v252, 9
	s_add_i32 s12, s12, s0
	s_lshl_b32 s8, s0, 14
	s_lshl_b32 s3, s90, 3
	s_branch .LBB0_44
